# layer-0 w_out bf16 copy deferred from the prologue to the slack of layer 0's in-projection phase (CUs 0-31, 96-159)
# speedup vs baseline: 1.0059x; 1.0006x over previous
; #define LAS __attribute__((address_space(3)))
; #define P (*({ CParams* q_ = kp; asm volatile("" : "+s"(q_)); q_; }))
; #define wave (__builtin_amdgcn_readfirstlane(tid >> 6))
; DI void p0_matrix(const float* W, const float* gain, int K, int N, bf16_t* WT, LAS float* scr, int nitems, int gw, int NGW, int lane) {
;     for (int it = gw; it < nitems; it += 4 * NGW) {
;         const int it2 = it + NGW, it3 = it + 2 * NGW, it4 = it + 3 * NGW; const bool h2 = it2 < nitems, h3 = it3 < nitems, h4 = it4 < nitems;
;         f32x4 va[8], vb[8], vc[8], vd[8];
;         p0_item_load(W, N, it, lane, va);
;         if (h2) p0_item_load(W, N, it2, lane, vb);
;         if (h3) p0_item_load(W, N, it3, lane, vc);
;         if (h4) p0_item_load(W, N, it4, lane, vd);
;         p0_item_store(va, gain, K, N, WT, scr, it, lane);
;         if (h2) p0_item_store(vb, gain, K, N, WT, scr, it2, lane);
;         if (h3) p0_item_store(vc, gain, K, N, WT, scr, it3, lane);
;         if (h4) p0_item_store(vd, gain, K, N, WT, scr, it4, lane);
;     }
; }
;     unsigned char* ws = P.ws;
;     LAS float* scr = (LAS float*)(lds + wave * 16384);
;     constexpr int I_IN = (DM / 64) * (NPROJ / 32), I_OUT = (DM / 64) * (DM / 32), I_KV = (DM / 64) * (NKV / 32);
;     if (which & 1) p0_matrix(P.w_in + (size_t)l * DM * NPROJ, P.norm_g + l * DM, DM, NPROJ, (bf16_t*)(ws + WS_WIN) + (size_t)l * NPROJ * DM, scr, I_IN, gw, NGW, lane);
;     if (which & 2) p0_matrix(P.w_out + (size_t)l * DM * DM, nullptr, DM, DM, (bf16_t*)(ws + WS_WOUT) + (size_t)l * DM * DM, scr, I_OUT, gw, NGW, lane);
.LBB0_86:
	s_cmpk_gt_i32 s17, 0x1fff
	s_branch .LBB0_101
	s_load_dwordx2 s[4:5], s[14:15], 0x88
	v_and_b32_e32 v2, 0x70, v135
	v_mov_b32_e32 v3, 0
	v_add_u32_e32 v5, s0, v2
	v_mul_u32_u24_e32 v4, 0x84, v136
	s_waitcnt lgkmcnt(0)
	v_lshl_add_u64 v[130:131], s[4:5], 0, v[2:3]
	v_and_b32_e32 v2, 56, v1
	v_mul_u32_u24_e32 v6, 0x84, v2
	v_lshlrev_b32_e32 v2, 1, v2
	v_lshl_add_u64 v[2:3], s[12:13], 0, v[2:3]
	s_mov_b64 s[4:5], 0xc200000
	v_lshl_add_u64 v[132:133], v[2:3], 0, s[4:5]
	v_lshlrev_b32_e32 v2, 2, v136
	v_or_b32_e32 v137, 8, v136
	v_or_b32_e32 v138, 16, v136
	v_or_b32_e32 v139, 24, v136
	v_add3_u32 v140, s0, v6, v2
	s_lshl_b32 s1, s76, 5
	s_lshl_b32 s2, s17, 5
	s_lshl_b32 s20, s76, 10
	s_lshl_b32 s21, s76, 4
	v_add_u32_e32 v141, v5, v4
	s_mov_b32 s22, s17
	s_branch .LBB0_89

; #define LAS __attribute__((address_space(3)))
; #define P (*({ CParams* q_ = kp; asm volatile("" : "+s"(q_)); q_; }))
; #define wave (__builtin_amdgcn_readfirstlane(tid >> 6))
;     unsigned char* ws = P.ws;
;     LAS float* scr = (LAS float*)(lds + wave * 16384);
;     constexpr int I_IN = (DM / 64) * (NPROJ / 32), I_OUT = (DM / 64) * (DM / 32), I_KV = (DM / 64) * (NKV / 32);
;     if (which & 1) p0_matrix(P.w_in + (size_t)l * DM * NPROJ, P.norm_g + l * DM, DM, NPROJ, (bf16_t*)(ws + WS_WIN) + (size_t)l * NPROJ * DM, scr, I_IN, gw, NGW, lane);
;     if (which & 2) p0_matrix(P.w_out + (size_t)l * DM * DM, nullptr, DM, DM, (bf16_t*)(ws + WS_WOUT) + (size_t)l * DM * DM, scr, I_OUT, gw, NGW, lane);
; __global__ void __launch_bounds__(NTHREADS, 2) fwd_megakernel(Params P_) {
;     ...
;         if (bx >= 160) { int t2 = threadIdx.x; asm volatile("" : "+v"(t2)); const int w2 = __builtin_amdgcn_readfirstlane(t2 >> 6);
;             convert_weights(P, 1, lds, (bx - 160) * NWAVES + w2, 96 * NWAVES, t2 & 63, w2, l == 0 ? 5 : 2); }
.LBB0_517:
	s_and_b64 vcc, exec, s[94:95]
	s_cbranch_vccz .LBB0_693
	s_cmp_ge_u32 s69, 160
	s_cbranch_scc0 .Lcv_group2
	s_mov_b32 s100, 0xe200000
	s_mov_b32 s101, 0x4000000
	v_mov_b32_e32 v0, v218
	s_mov_b64 s[12:13], s[74:75]
	v_readfirstlane_b32 s0, v0
	s_ashr_i32 s2, s0, 6
	v_readlane_b32 s0, v254, 46
	s_add_i32 s6, s0, s2
	s_load_dwordx2 s[10:11], s[12:13], 0xa0
	s_and_b64 s[0:1], s[94:95], exec
	s_cselect_b32 s1, 7, 0
	s_lshl_b32 s0, s2, 14
	s_add_i32 s0, s0, 0
	s_bitcmp0_b32 s1, 0
	v_and_b32_e32 v140, 63, v0
	s_cbranch_scc1 .LBB0_598
	s_cmpk_gt_i32 s6, 0x5fff
	s_cbranch_scc1 .LBB0_598
	s_load_dwordx4 s[20:23], s[12:13], 0x18
	v_lshlrev_b32_e32 v0, 4, v140
	v_and_b32_e32 v196, 0x70, v0
	s_mov_b64 s[2:3], 0xc000000
	v_lshrrev_b32_e32 v141, 3, v140
	s_waitcnt lgkmcnt(0)
	v_lshl_add_u64 v[0:1], s[22:23], 0, v[196:197]
	v_lshl_add_u64 v[132:133], v[0:1], 0, s[2:3]
	v_lshlrev_b32_e32 v0, 3, v140
	v_and_b32_e32 v0, 56, v0
	s_add_u32 s14, s20, 0x4000
	v_add_u32_e32 v2, s0, v196
	s_movk_i32 s2, 0x84
	v_lshlrev_b32_e32 v196, 1, v0
	s_addc_u32 s15, s21, 0
	v_mad_u32_u24 v4, v141, s2, v227
	v_mul_u32_u24_e32 v5, 0x84, v0
	v_lshl_add_u64 v[0:1], s[10:11], 0, v[196:197]
	s_mov_b64 s[2:3], 0x6200000
	s_cmp_lg_u64 s[20:21], 0
	v_mul_u32_u24_e32 v3, 0x84, v141
	v_lshl_add_u64 v[134:135], v[0:1], 0, s[2:3]
	v_lshlrev_b32_e32 v0, 2, v141
	s_cselect_b64 s[18:19], -1, 0
	v_or_b32_e32 v142, 8, v141
	v_or_b32_e32 v143, 16, v141
	v_or_b32_e32 v144, 24, v141
	v_or_b32_e32 v145, 32, v141
	v_or_b32_e32 v146, 40, v141
	v_or_b32_e32 v147, 48, v141
	v_or_b32_e32 v148, 56, v141
	v_add3_u32 v149, s0, v5, v0
	s_lshl_b32 s2, s6, 5
	v_add_u32_e32 v150, v2, v3
	v_add_u32_e32 v151, v2, v4
	s_mov_b32 s3, s6
	s_branch .LBB0_523

; #define LAS __attribute__((address_space(3)))
; #define P (*({ CParams* q_ = kp; asm volatile("" : "+s"(q_)); q_; }))
; #define wave (__builtin_amdgcn_readfirstlane(tid >> 6))
; DI void p0_matrix(const float* W, const float* gain, int K, int N, bf16_t* WT, LAS float* scr, int nitems, int gw, int NGW, int lane) {
;     for (int it = gw; it < nitems; it += 4 * NGW) {
;         const int it2 = it + NGW, it3 = it + 2 * NGW, it4 = it + 3 * NGW; const bool h2 = it2 < nitems, h3 = it3 < nitems, h4 = it4 < nitems;
;         f32x4 va[8], vb[8], vc[8], vd[8];
;         p0_item_load(W, N, it, lane, va);
;         if (h2) p0_item_load(W, N, it2, lane, vb);
;         if (h3) p0_item_load(W, N, it3, lane, vc);
;         if (h4) p0_item_load(W, N, it4, lane, vd);
;         p0_item_store(va, gain, K, N, WT, scr, it, lane);
;         if (h2) p0_item_store(vb, gain, K, N, WT, scr, it2, lane);
;         if (h3) p0_item_store(vc, gain, K, N, WT, scr, it3, lane);
;         if (h4) p0_item_store(vd, gain, K, N, WT, scr, it4, lane);
;     }
; }
;     unsigned char* ws = P.ws;
;     LAS float* scr = (LAS float*)(lds + wave * 16384);
;     constexpr int I_IN = (DM / 64) * (NPROJ / 32), I_OUT = (DM / 64) * (DM / 32), I_KV = (DM / 64) * (NKV / 32);
;     if (which & 1) p0_matrix(P.w_in + (size_t)l * DM * NPROJ, P.norm_g + l * DM, DM, NPROJ, (bf16_t*)(ws + WS_WIN) + (size_t)l * NPROJ * DM, scr, I_IN, gw, NGW, lane);
;     if (which & 2) p0_matrix(P.w_out + (size_t)l * DM * DM, nullptr, DM, DM, (bf16_t*)(ws + WS_WOUT) + (size_t)l * DM * DM, scr, I_OUT, gw, NGW, lane);
.LBB0_598:
	s_bitcmp0_b32 s1, 1
	s_cselect_b64 s[2:3], -1, 0
	s_cmpk_gt_i32 s6, 0x1fff
	s_cselect_b64 s[8:9], -1, 0
	s_or_b64 s[2:3], s[2:3], s[8:9]
	s_and_b64 vcc, exec, s[2:3]
	s_cbranch_vccnz .LBB0_613
	s_load_dwordx2 s[2:3], s[12:13], 0x88
	v_lshlrev_b32_e32 v0, 4, v140
	v_and_b32_e32 v196, 0x70, v0
	v_add_u32_e32 v2, s0, v196
	v_lshrrev_b32_e32 v132, 3, v140
	s_waitcnt lgkmcnt(0)
	v_lshl_add_u64 v[0:1], s[2:3], 0, v[196:197]
	s_mov_b32 s2, s101
	s_mov_b32 s3, 0
	v_lshl_add_u64 v[128:129], v[0:1], 0, s[2:3]
	v_lshlrev_b32_e32 v0, 3, v140
	v_and_b32_e32 v0, 56, v0
	v_lshlrev_b32_e32 v196, 1, v0
	v_mul_u32_u24_e32 v4, 0x84, v0
	v_lshl_add_u64 v[0:1], s[10:11], 0, v[196:197]
	s_mov_b32 s2, s100
	s_mov_b32 s3, 0
	v_mul_u32_u24_e32 v3, 0x84, v132
	v_lshl_add_u64 v[130:131], v[0:1], 0, s[2:3]
	v_lshlrev_b32_e32 v0, 2, v132
	v_or_b32_e32 v133, 8, v132
	v_or_b32_e32 v134, 16, v132
	v_or_b32_e32 v135, 24, v132
	v_add3_u32 v136, s0, v4, v0
	s_lshl_b32 s1, s6, 5
	v_add_u32_e32 v137, v2, v3
	s_mov_b32 s2, s6
	s_branch .LBB0_601

; #define LAS __attribute__((address_space(3)))
; #define P (*({ CParams* q_ = kp; asm volatile("" : "+s"(q_)); q_; }))
; #define wave (__builtin_amdgcn_readfirstlane(tid >> 6))
; DI void p0_matrix(const float* W, const float* gain, int K, int N, bf16_t* WT, LAS float* scr, int nitems, int gw, int NGW, int lane) {
;     for (int it = gw; it < nitems; it += 4 * NGW) {
;         const int it2 = it + NGW, it3 = it + 2 * NGW, it4 = it + 3 * NGW; const bool h2 = it2 < nitems, h3 = it3 < nitems, h4 = it4 < nitems;
;         f32x4 va[8], vb[8], vc[8], vd[8];
;         p0_item_load(W, N, it, lane, va);
;         if (h2) p0_item_load(W, N, it2, lane, vb);
;         if (h3) p0_item_load(W, N, it3, lane, vc);
;         if (h4) p0_item_load(W, N, it4, lane, vd);
;         p0_item_store(va, gain, K, N, WT, scr, it, lane);
;         if (h2) p0_item_store(vb, gain, K, N, WT, scr, it2, lane);
;         if (h3) p0_item_store(vc, gain, K, N, WT, scr, it3, lane);
;         if (h4) p0_item_store(vd, gain, K, N, WT, scr, it4, lane);
;     }
; }
;     unsigned char* ws = P.ws;
;     LAS float* scr = (LAS float*)(lds + wave * 16384);
;     constexpr int I_IN = (DM / 64) * (NPROJ / 32), I_OUT = (DM / 64) * (DM / 32), I_KV = (DM / 64) * (NKV / 32);
;     if (which & 1) p0_matrix(P.w_in + (size_t)l * DM * NPROJ, P.norm_g + l * DM, DM, NPROJ, (bf16_t*)(ws + WS_WIN) + (size_t)l * NPROJ * DM, scr, I_IN, gw, NGW, lane);
;     if (which & 2) p0_matrix(P.w_out + (size_t)l * DM * DM, nullptr, DM, DM, (bf16_t*)(ws + WS_WOUT) + (size_t)l * DM * DM, scr, I_OUT, gw, NGW, lane);
;     if (which & 4) p0_matrix(P.w_kv + (size_t)l * DM * NKV, P.mem_ng + l * DM, DM, NKV, (bf16_t*)(ws + WS_WKV) + (size_t)l * NKV * DM, scr, I_KV, gw, NGW, lane);
.LBB0_613:
	s_cmp_eq_u32 s101, 0
	s_cbranch_scc1 .LBB0_693
	s_andn2_b64 vcc, exec, s[94:95]
	s_cbranch_vccnz .LBB0_693
	s_cmpk_gt_i32 s6, 0xfff
	s_cbranch_scc1 .LBB0_693
	s_load_dwordx4 s[20:23], s[12:13], 0x78
	v_lshlrev_b32_e32 v0, 4, v140
	v_and_b32_e32 v196, 0x70, v0
	s_mov_b64 s[2:3], 0x2000000
	v_add_u32_e32 v2, s0, v196
	s_waitcnt lgkmcnt(0)
	v_lshl_add_u64 v[0:1], s[22:23], 0, v[196:197]
	v_lshl_add_u64 v[132:133], v[0:1], 0, s[2:3]
	v_lshlrev_b32_e32 v0, 3, v140
	v_and_b32_e32 v0, 56, v0
	s_add_u32 s12, s20, 0x4000
	v_lshlrev_b32_e32 v196, 1, v0
	v_lshrrev_b32_e32 v141, 3, v140
	s_addc_u32 s13, s21, 0
	s_movk_i32 s1, 0x84
	v_mul_u32_u24_e32 v5, 0x84, v0
	v_lshl_add_u64 v[0:1], s[10:11], 0, v[196:197]
	s_mov_b64 s[2:3], 0x11200000
	s_cmp_lg_u64 s[20:21], 0
	v_mul_u32_u24_e32 v3, 0x84, v141
	v_mad_u32_u24 v4, v141, s1, v227
	v_lshl_add_u64 v[134:135], v[0:1], 0, s[2:3]
	v_lshlrev_b32_e32 v0, 2, v141
	s_cselect_b64 s[14:15], -1, 0
	v_or_b32_e32 v142, 8, v141
	v_or_b32_e32 v143, 16, v141
	v_or_b32_e32 v144, 24, v141
	v_or_b32_e32 v145, 32, v141
	v_or_b32_e32 v146, 40, v141
	v_or_b32_e32 v147, 48, v141
	v_or_b32_e32 v148, 56, v141
	v_add3_u32 v140, s0, v5, v0
	s_lshl_b32 s0, s6, 5
	v_add_u32_e32 v149, v2, v3
	v_add_u32_e32 v150, v2, v4
	s_branch .LBB0_618

; #define P (*({ CParams* q_ = kp; asm volatile("" : "+s"(q_)); q_; }))
; __global__ void __launch_bounds__(NTHREADS, 2) fwd_megakernel(Params P_) {
;     ...
;         if (bx >= 160) { int t2 = threadIdx.x; asm volatile("" : "+v"(t2)); const int w2 = __builtin_amdgcn_readfirstlane(t2 >> 6);
;             convert_weights(P, 1, lds, (bx - 160) * NWAVES + w2, 96 * NWAVES, t2 & 63, w2, l == 0 ? 5 : 2); }
.Lcv_group2:
	s_cmp_lt_u32 s69, 32
	s_cbranch_scc1 .Lcv_g2_chain
	s_cmp_lt_u32 s69, 96
	s_cbranch_scc1 .LBB0_693
	s_add_i32 s6, s69, -64
	s_branch .Lcv_g2_go

; #define LAS __attribute__((address_space(3)))
; #define P (*({ CParams* q_ = kp; asm volatile("" : "+s"(q_)); q_; }))
; #define wave (__builtin_amdgcn_readfirstlane(tid >> 6))
;     unsigned char* ws = P.ws;
;     LAS float* scr = (LAS float*)(lds + wave * 16384);
;     constexpr int I_IN = (DM / 64) * (NPROJ / 32), I_OUT = (DM / 64) * (DM / 32), I_KV = (DM / 64) * (NKV / 32);
;     if (which & 1) p0_matrix(P.w_in + (size_t)l * DM * NPROJ, P.norm_g + l * DM, DM, NPROJ, (bf16_t*)(ws + WS_WIN) + (size_t)l * NPROJ * DM, scr, I_IN, gw, NGW, lane);
; __global__ void __launch_bounds__(NTHREADS, 2) fwd_megakernel(Params P_) {
;     ...
;         if (bx >= 160) { int t2 = threadIdx.x; asm volatile("" : "+v"(t2)); const int w2 = __builtin_amdgcn_readfirstlane(t2 >> 6);
;             convert_weights(P, 1, lds, (bx - 160) * NWAVES + w2, 96 * NWAVES, t2 & 63, w2, l == 0 ? 5 : 2); }
.Lcv_g2_go:
	s_lshl_b32 s6, s6, 3
	s_mov_b32 s100, 0xc200000
	s_mov_b32 s101, 0
	v_mov_b32_e32 v0, v218
	s_mov_b64 s[12:13], s[74:75]
	v_readfirstlane_b32 s0, v0
	s_ashr_i32 s2, s0, 6
	s_add_i32 s6, s6, s2
	s_load_dwordx2 s[10:11], s[12:13], 0xa0
	s_mov_b32 s1, 2
	s_lshl_b32 s0, s2, 14
	s_add_i32 s0, s0, 0
	v_and_b32_e32 v140, 63, v0
	s_branch .LBB0_598
